# latent Hyena K loop: B fragments shared by the 4 waves through double-buffered LDS (each wave loads 1 of 4, one barrier per 128-step iteration)
# speedup vs baseline: 1.0043x; 1.0043x over previous
; DI void hyena_item_lat(const Params& p, int l, int it) {
;     ...
;   const int c = it >> 2, f = l, L = 2048, posoff = CTXL;
;   const int tt0 = (it & 3) * 512 + w * 128;
;   const u16* R0 = WSP(const u16, OFF_RF) + ((size_t)(f * 256 + c) * 2) * RSTR;
;   const u16* R1 = R0 + RSTR;
;   const u16* UT = WSP(const u16, OFF_UT);
;   const int l16 = lane & 15, kg = lane >> 4;
;   f32x4 acc[8];
; #pragma unroll
;   for (int i = 0; i < 8; ++i) acc[i] = (f32x4){0.f, 0.f, 0.f, 0.f};
;   const u16* ub = UT + ((size_t)(c * 16 + l16)) * TPB + posoff + kg * 8;
;   const u16* rsel = (l16 & 1) ? (R1 - 1) : R0;
;   const int nb = L - (tt0 + l16) + kg * 8;
;   union AF { u32 u[4]; bf16x8 v; };
;   AF a[8];
;     ...
; #pragma unroll
;   for (int i = 2; i < 8; ++i) HY_LOADA(a[i], nb - 16 * i)
; #pragma unroll 1
;   for (int sb = 0; sb < L; sb += 128) {
; #pragma unroll
;     for (int u = 0; u < 4; ++u) {
;       const int s0 = sb + 32 * u;
;       HY_LOADA(a[(0 - 2 * u) & 7], nb + s0)
;       HY_LOADA(a[(1 - 2 * u) & 7], nb - 16 + s0)
;       const bf16x8 bfrag = *(const bf16x8*)(ub + s0);
; #pragma unroll
;       for (int i = 0; i < 8; ++i) acc[i] = __builtin_amdgcn_mfma_f32_16x16x32_bf16(a[(i - 2 * u) & 7].v, bfrag, acc[i], 0, 0, 0);
;     }
;   }
.LBB0_1137:
	s_andn2_b64 vcc, exec, s[34:35]
	s_cbranch_vccnz .LBB0_1141
	s_ashr_i32 s34, s13, 2
	v_mov_b32_e32 v0, v218
	v_mov_b32_e32 v1, v218
	s_add_i32 s36, s34, s42
	s_lshl_b32 s13, s13, 9
	s_ashr_i32 s37, s36, 31
	s_mul_i32 s38, s36, 0x4040
	v_readlane_b32 s16, v254, 47
	v_lshlrev_b32_e32 v1, 1, v1
	s_mul_hi_i32 s35, s36, 0x4040
	v_readlane_b32 s17, v254, 48
	s_add_u32 s38, s16, s38
	v_and_b32_e32 v1, 0xffffff80, v1
	s_addc_u32 s39, s17, s35
	s_and_b32 s13, s13, 0x600
	v_add_u32_e32 v63, s13, v1
	v_and_b32_e32 v62, 15, v0
	v_bfe_u32 v64, v0, 4, 2
	v_bfe_i32 v0, v0, 0, 1
	v_lshlrev_b32_e32 v1, 3, v64
	v_and_b32_e32 v172, 0x201e, v0
	v_or_b32_e32 v0, v63, v62
	v_sub_u32_e32 v58, v1, v0
	v_lshl_add_u64 v[56:57], s[38:39], 0, v[172:173]
	v_ashrrev_i32_e32 v59, 31, v58
	v_lshl_add_u64 v[0:1], v[58:59], 1, v[56:57]
	global_load_dwordx4 v[40:43], v[0:1], off offset:4032
	global_load_dwordx4 v[44:47], v[0:1], off offset:4000
	global_load_dwordx4 v[32:35], v[0:1], off offset:3968
	global_load_dwordx4 v[36:39], v[0:1], off offset:3936
	global_load_dwordx4 v[48:51], v[0:1], off offset:3904
	global_load_dwordx4 v[52:55], v[0:1], off offset:3872
	s_lshl_b32 s35, s34, 4
	v_or_b32_e32 v59, s35, v62
	v_mad_i64_i32 v[0:1], s[38:39], v59, s9, 0
	v_readlane_b32 s16, v255, 56
	v_lshl_or_b32 v0, v64, 4, v0
	v_readlane_b32 s17, v255, 57
	v_mov_b32_e32 v28, 0
	s_mov_b64 s[46:47], s[20:21]
	s_movk_i32 s13, 0xff80
	v_lshl_add_u64 v[60:61], s[16:17], 0, v[0:1]
	v_mov_b32_e32 v29, v28
	v_mov_b32_e32 v30, v28
	v_mov_b32_e32 v31, v28
	v_mov_b32_e32 v24, v28
	v_mov_b32_e32 v25, v28
	v_mov_b32_e32 v26, v28
	v_mov_b32_e32 v27, v28
	v_mov_b32_e32 v20, v28
	v_mov_b32_e32 v21, v28
	v_mov_b32_e32 v22, v28
	v_mov_b32_e32 v23, v28
	v_mov_b32_e32 v16, v28
	v_mov_b32_e32 v17, v28
	v_mov_b32_e32 v18, v28
	v_mov_b32_e32 v19, v28
	v_mov_b32_e32 v12, v28
	v_mov_b32_e32 v13, v28
	v_mov_b32_e32 v14, v28
	v_mov_b32_e32 v15, v28
	v_mov_b32_e32 v8, v28
	v_mov_b32_e32 v9, v28
	v_mov_b32_e32 v10, v28
	v_mov_b32_e32 v11, v28
	v_mov_b32_e32 v4, v28
	v_mov_b32_e32 v5, v28
	v_mov_b32_e32 v6, v28
	v_mov_b32_e32 v7, v28
	v_mov_b32_e32 v0, v28
	v_mov_b32_e32 v1, v28
	v_mov_b32_e32 v2, v28
	v_mov_b32_e32 v3, v28
	v_and_b32_e32 v92, 0xc0, v218
	v_mov_b32_e32 v93, 0
	v_lshlrev_b32_e32 v94, 4, v218
	v_and_b32_e32 v95, 63, v218
	v_lshl_add_u64 v[90:91], v[92:93], 0, v[60:61]
	v_lshlrev_b32_e32 v95, 4, v95
	global_load_dwordx4 v[82:85], v[90:91], off offset:-192
.LBB0_1139:
	s_waitcnt vmcnt(0)
	ds_write_b128 v94, v[82:85]
	s_waitcnt lgkmcnt(0)
	s_barrier
	ds_read_b128 v[66:69], v95
	ds_read_b128 v[70:73], v95 offset:1024
	ds_read_b128 v[86:89], v95 offset:2048
	ds_read_b128 v[74:77], v95 offset:3072
	v_xor_b32_e32 v94, 0x1000, v94
	v_xor_b32_e32 v95, 0x1000, v95
	s_mov_b64 s[38:39], 0x100
	s_waitcnt lgkmcnt(0)
	v_mfma_f32_16x16x32_bf16 v[4:7], v[48:51], v[66:69], v[4:7]
	v_add_u32_e32 v49, s13, v58
	v_add_u32_e32 v48, 0x880, v49
	v_add_u32_e32 v50, 0x870, v49
	v_mfma_f32_16x16x32_bf16 v[0:3], v[52:55], v[66:69], v[0:3]
	v_ashrrev_i32_e32 v49, 31, v48
	v_ashrrev_i32_e32 v51, 31, v50
	v_lshl_add_u64 v[78:79], v[48:49], 1, v[56:57]
	v_lshl_add_u64 v[80:81], v[50:51], 1, v[56:57]
	v_mfma_f32_16x16x32_bf16 v[12:15], v[32:35], v[66:69], v[12:15]
	global_load_dwordx4 v[48:51], v[78:79], off offset:64
	global_load_dwordx4 v[52:55], v[80:81], off offset:64
	s_addk_i32 s13, 0x80
	v_mfma_f32_16x16x32_bf16 v[8:11], v[36:39], v[66:69], v[8:11]
	s_cmpk_lt_u32 s13, 0x780
	v_mfma_f32_16x16x32_bf16 v[4:7], v[32:35], v[70:73], v[4:7]
	global_load_dwordx4 v[32:35], v[78:79], off
	v_mfma_f32_16x16x32_bf16 v[0:3], v[36:39], v[70:73], v[0:3]
	global_load_dwordx4 v[36:39], v[80:81], off
	v_mfma_f32_16x16x32_bf16 v[20:23], v[40:43], v[66:69], v[20:23]
	v_mfma_f32_16x16x32_bf16 v[16:19], v[44:47], v[66:69], v[16:19]
	s_waitcnt vmcnt(1)
	v_mfma_f32_16x16x32_bf16 v[28:31], v[32:35], v[66:69], v[28:31]
	s_waitcnt vmcnt(0)
	v_mfma_f32_16x16x32_bf16 v[24:27], v[36:39], v[66:69], v[24:27]
	global_load_dwordx4 v[82:85], v[90:91], off offset:64
	v_lshl_add_u64 v[90:91], v[90:91], 0, s[38:39]
	v_lshl_add_u64 v[60:61], v[60:61], 0, s[38:39]
	v_mfma_f32_16x16x32_bf16 v[12:15], v[40:43], v[70:73], v[12:15]
	v_mfma_f32_16x16x32_bf16 v[8:11], v[44:47], v[70:73], v[8:11]
	v_mfma_f32_16x16x32_bf16 v[20:23], v[32:35], v[70:73], v[20:23]
	v_mfma_f32_16x16x32_bf16 v[16:19], v[36:39], v[70:73], v[16:19]
	v_mfma_f32_16x16x32_bf16 v[28:31], v[48:51], v[70:73], v[28:31]
	v_mfma_f32_16x16x32_bf16 v[24:27], v[52:55], v[70:73], v[24:27]
	v_mfma_f32_16x16x32_bf16 v[4:7], v[40:43], v[86:89], v[4:7]
	global_load_dwordx4 v[40:43], v[78:79], off offset:192
	v_mfma_f32_16x16x32_bf16 v[0:3], v[44:47], v[86:89], v[0:3]
	global_load_dwordx4 v[44:47], v[80:81], off offset:192
	v_mfma_f32_16x16x32_bf16 v[12:15], v[32:35], v[86:89], v[12:15]
	v_mfma_f32_16x16x32_bf16 v[8:11], v[36:39], v[86:89], v[8:11]
	v_mfma_f32_16x16x32_bf16 v[4:7], v[32:35], v[74:77], v[4:7]
	global_load_dwordx4 v[32:35], v[78:79], off offset:128
	v_mfma_f32_16x16x32_bf16 v[0:3], v[36:39], v[74:77], v[0:3]
	global_load_dwordx4 v[36:39], v[80:81], off offset:128
	v_mfma_f32_16x16x32_bf16 v[20:23], v[48:51], v[86:89], v[20:23]
	v_mfma_f32_16x16x32_bf16 v[16:19], v[52:55], v[86:89], v[16:19]
	v_mfma_f32_16x16x32_bf16 v[12:15], v[48:51], v[74:77], v[12:15]
	v_mfma_f32_16x16x32_bf16 v[8:11], v[52:55], v[74:77], v[8:11]
	s_waitcnt vmcnt(1)
	v_mfma_f32_16x16x32_bf16 v[28:31], v[32:35], v[86:89], v[28:31]
	s_waitcnt vmcnt(0)
	v_mfma_f32_16x16x32_bf16 v[24:27], v[36:39], v[86:89], v[24:27]
	v_mfma_f32_16x16x32_bf16 v[20:23], v[32:35], v[74:77], v[20:23]
	v_mfma_f32_16x16x32_bf16 v[16:19], v[36:39], v[74:77], v[16:19]
	v_mfma_f32_16x16x32_bf16 v[28:31], v[40:43], v[74:77], v[28:31]
	v_mfma_f32_16x16x32_bf16 v[24:27], v[44:47], v[74:77], v[24:27]
	s_cbranch_scc1 .LBB0_1139
; DI float bf2f(u16 v) { return __uint_as_float(((u32)v) << 16); }
; DI void hyena_item_lat(const Params& p, int l, int it) {
;     ...
;   float ssq = 0.f;
;   for (int t = 0; t < 32; ++t) ssq += WSP(const float, OFF_PART)[(size_t)(f * 32 + t) * 256 + c];
;   const float scale = rsqrtf(ssq + EPSF);
;   const float bias = p.in[I_HYBIAS][l * 256 + c];
;   const u16* X1C = WSP(const u16, OFF_X1C);
;   u16* YM = WSP(u16, OFF_ACT);
;   const int b = l16;
; #pragma unroll
;   for (int i = 0; i < 8; ++i)
; #pragma unroll
;     for (int r = 0; r < 4; ++r) {
;       const int t = tt0 + 16 * i + kg * 4 + r;
;       const size_t row = (size_t)b * TPB + posoff + t;
;       const float uu = bf2f(UT[((size_t)(c * 16 + b)) * TPB + posoff + t]);
	s_waitcnt vmcnt(0)
	v_mov_b64_e32 v[32:33], s[96:97]
	v_mad_i64_i32 v[32:33], s[38:39], v59, s9, v[32:33]
	s_mov_b64 s[38:39], 0x15600200
	s_ashr_i32 s35, s34, 31
	v_lshl_add_u64 v[32:33], v[32:33], 0, s[38:39]
	s_lshl_b64 s[38:39], s[34:35], 2
	s_add_u32 s38, s43, s38
	s_addc_u32 s39, s44, s39
	global_load_dword v38, v173, s[38:39]
	global_load_dword v39, v173, s[38:39] offset:1024
	global_load_dword v40, v173, s[38:39] offset:2048
	global_load_dword v41, v173, s[38:39] offset:3072
	v_mov_b32_e32 v92, 0x1000
	global_load_dword v42, v92, s[38:39]
	global_load_dword v43, v92, s[38:39] offset:1024
	global_load_dword v44, v92, s[38:39] offset:2048
	global_load_dword v45, v92, s[38:39] offset:3072
	v_mov_b32_e32 v92, 0x2000
	global_load_dword v46, v92, s[38:39]
	global_load_dword v47, v92, s[38:39] offset:1024
	global_load_dword v48, v92, s[38:39] offset:2048
	global_load_dword v49, v92, s[38:39] offset:3072
	v_mov_b32_e32 v92, 0x3000
	global_load_dword v50, v92, s[38:39]
	global_load_dword v51, v92, s[38:39] offset:1024
	global_load_dword v52, v92, s[38:39] offset:2048
	global_load_dword v53, v92, s[38:39] offset:3072
	v_mov_b32_e32 v92, 0x4000
	global_load_dword v54, v92, s[38:39]
	global_load_dword v55, v92, s[38:39] offset:1024
	global_load_dword v56, v92, s[38:39] offset:2048
	global_load_dword v57, v92, s[38:39] offset:3072
	v_mov_b32_e32 v92, 0x5000
	global_load_dword v58, v92, s[38:39]
	global_load_dword v65, v92, s[38:39] offset:1024
	global_load_dword v66, v92, s[38:39] offset:2048
	global_load_dword v67, v92, s[38:39] offset:3072
	v_mov_b32_e32 v92, 0x6000
	global_load_dword v68, v92, s[38:39]
	global_load_dword v69, v92, s[38:39] offset:1024
	global_load_dword v70, v92, s[38:39] offset:2048
	global_load_dword v71, v92, s[38:39] offset:3072
	v_mov_b32_e32 v92, 0x7000
	global_load_dword v72, v92, s[38:39]
	global_load_dword v73, v92, s[38:39] offset:1024
	global_load_dword v74, v92, s[38:39] offset:2048
	global_load_dword v75, v92, s[38:39] offset:3072
	v_readlane_b32 s16, v254, 29
	s_lshl_b64 s[36:37], s[36:37], 2
	v_readlane_b32 s18, v254, 31
	v_readlane_b32 s19, v254, 32
	s_add_u32 s36, s18, s36
	s_addc_u32 s37, s19, s37
	global_load_dword v37, v173, s[36:37]
	s_movk_i32 s13, 0x900
	v_lshl_or_b32 v34, v64, 2, v63
	v_mov_b32_e32 v35, 0x100
	v_mad_u32_u24 v172, v62, s13, v35
	v_mov_b32_e32 v35, 0
	v_lshl_add_u64 v[94:95], v[34:35], 1, v[32:33]
	global_load_dwordx2 v[76:77], v[94:95], off
	global_load_dwordx2 v[78:79], v[94:95], off offset:32
	global_load_dwordx2 v[80:81], v[94:95], off offset:64
	global_load_dwordx2 v[82:83], v[94:95], off offset:96
	global_load_dwordx2 v[84:85], v[94:95], off offset:128
	global_load_dwordx2 v[86:87], v[94:95], off offset:160
	global_load_dwordx2 v[88:89], v[94:95], off offset:192
	global_load_dwordx2 v[90:91], v[94:95], off offset:224
	v_readlane_b32 s17, v254, 30
	s_lshl_b64 s[34:35], s[34:35], 1
	v_readlane_b32 s16, v255, 42
	v_readlane_b32 s17, v255, 43
	v_readlane_b32 s20, v254, 33
	v_readlane_b32 s21, v254, 34
	v_readlane_b32 s24, v254, 37
	v_readlane_b32 s18, v254, 10
	s_mov_b64 s[20:21], s[46:47]
	s_mov_b32 s24, s64
	v_readlane_b32 s22, v254, 35
	v_readlane_b32 s23, v254, 36
	v_readlane_b32 s25, v254, 38
	v_readlane_b32 s26, v254, 39
	v_readlane_b32 s27, v254, 40
	v_readlane_b32 s28, v254, 41
	v_readlane_b32 s29, v254, 42
	v_readlane_b32 s30, v254, 43
	v_readlane_b32 s31, v254, 44
	v_readlane_b32 s19, v254, 11
	s_add_u32 s38, s16, s34
	s_addc_u32 s39, s17, s35
	s_add_u32 s36, s6, s34
	s_addc_u32 s37, s7, s35
	v_lshlrev_b32_e32 v142, 13, v62
	v_lshl_add_u32 v142, v34, 2, v142
	s_waitcnt vmcnt(0)
; DI u16 f2bf(float x) { u32 u = __float_as_uint(x); u += 0x7fffu + ((u >> 16) & 1u); return (u16)(u >> 16); }
; DI float bf2f(u16 v) { return __uint_as_float(((u32)v) << 16); }
; DI void hyena_item_lat(const Params& p, int l, int it) {
;     ...
;   float ssq = 0.f;
;   for (int t = 0; t < 32; ++t) ssq += WSP(const float, OFF_PART)[(size_t)(f * 32 + t) * 256 + c];
;   const float scale = rsqrtf(ssq + EPSF);
;   const float bias = p.in[I_HYBIAS][l * 256 + c];
;   const u16* X1C = WSP(const u16, OFF_X1C);
;   u16* YM = WSP(u16, OFF_ACT);
;   const int b = l16;
; #pragma unroll
;   for (int i = 0; i < 8; ++i)
; #pragma unroll
;     for (int r = 0; r < 4; ++r) {
;       const int t = tt0 + 16 * i + kg * 4 + r;
;       const size_t row = (size_t)b * TPB + posoff + t;
;       const float uu = bf2f(UT[((size_t)(c * 16 + b)) * TPB + posoff + t]);
;       const float x1 = bf2f(X1C[row * 256 + c]);
;       YM[row * 1024 + c] = f2bf(x1 * (scale * acc[i][r] + bias * uu));
;     }
	v_add_f32_e32 v36, 0, v38
	v_add_f32_e32 v36, v36, v39
	v_add_f32_e32 v36, v36, v40
	v_add_f32_e32 v36, v36, v41
	v_add_f32_e32 v36, v36, v42
	v_add_f32_e32 v36, v36, v43
	v_add_f32_e32 v36, v36, v44
	v_add_f32_e32 v36, v36, v45
	v_add_f32_e32 v36, v36, v46
	v_add_f32_e32 v36, v36, v47
	v_add_f32_e32 v36, v36, v48
	v_add_f32_e32 v36, v36, v49
	v_add_f32_e32 v36, v36, v50
	v_add_f32_e32 v36, v36, v51
	v_add_f32_e32 v36, v36, v52
	v_add_f32_e32 v36, v36, v53
	v_add_f32_e32 v36, v36, v54
	v_add_f32_e32 v36, v36, v55
	v_add_f32_e32 v36, v36, v56
	v_add_f32_e32 v36, v36, v57
	v_add_f32_e32 v36, v36, v58
	v_add_f32_e32 v36, v36, v65
	v_add_f32_e32 v36, v36, v66
	v_add_f32_e32 v36, v36, v67
	v_add_f32_e32 v36, v36, v68
	v_add_f32_e32 v36, v36, v69
	v_add_f32_e32 v36, v36, v70
	v_add_f32_e32 v36, v36, v71
	v_add_f32_e32 v36, v36, v72
	v_add_f32_e32 v36, v36, v73
	v_add_f32_e32 v36, v36, v74
	v_add_f32_e32 v36, v36, v75
	s_mov_b32 s13, 0x800000
	v_add_f32_e32 v36, 0x358637bd, v36
	v_cmp_gt_f32_e32 vcc, s13, v36
	v_mul_f32_e32 v35, 0x4b800000, v36
	s_movk_i32 s13, 0x900
	s_nop 0
	v_cndmask_b32_e32 v36, v36, v35, vcc
	v_rsq_f32_e32 v36, v36
	s_nop 0
	v_mul_f32_e32 v35, 0x45800000, v36
	v_cndmask_b32_e32 v36, v36, v35, vcc
	v_lshlrev_b32_e32 v92, 16, v76
	v_mul_f32_e32 v92, v37, v92
	v_fmac_f32_e32 v92, v28, v36
	v_mov_b32_e32 v28, v92
	v_and_b32_e32 v92, 0xffff0000, v76
	v_mul_f32_e32 v92, v37, v92
	v_fmac_f32_e32 v92, v29, v36
	v_mov_b32_e32 v29, v92
	v_lshlrev_b32_e32 v92, 16, v77
	v_mul_f32_e32 v92, v37, v92
	v_fmac_f32_e32 v92, v30, v36
	v_mov_b32_e32 v30, v92
	v_and_b32_e32 v92, 0xffff0000, v77
	v_mul_f32_e32 v92, v37, v92
	v_fmac_f32_e32 v92, v31, v36
	v_mov_b32_e32 v31, v92
	v_lshlrev_b32_e32 v92, 16, v78
	v_mul_f32_e32 v92, v37, v92
	v_fmac_f32_e32 v92, v24, v36
	v_mov_b32_e32 v24, v92
	v_and_b32_e32 v92, 0xffff0000, v78
	v_mul_f32_e32 v92, v37, v92
	v_fmac_f32_e32 v92, v25, v36
	v_mov_b32_e32 v25, v92
	v_lshlrev_b32_e32 v92, 16, v79
	v_mul_f32_e32 v92, v37, v92
	v_fmac_f32_e32 v92, v26, v36
	v_mov_b32_e32 v26, v92
	v_and_b32_e32 v92, 0xffff0000, v79
	v_mul_f32_e32 v92, v37, v92
	v_fmac_f32_e32 v92, v27, v36
	v_mov_b32_e32 v27, v92
	v_lshlrev_b32_e32 v92, 16, v80
	v_mul_f32_e32 v92, v37, v92
	v_fmac_f32_e32 v92, v20, v36
	v_mov_b32_e32 v20, v92
	v_and_b32_e32 v92, 0xffff0000, v80
	v_mul_f32_e32 v92, v37, v92
	v_fmac_f32_e32 v92, v21, v36
	v_mov_b32_e32 v21, v92
	v_lshlrev_b32_e32 v92, 16, v81
	v_mul_f32_e32 v92, v37, v92
	v_fmac_f32_e32 v92, v22, v36
	v_mov_b32_e32 v22, v92
	v_and_b32_e32 v92, 0xffff0000, v81
	v_mul_f32_e32 v92, v37, v92
	v_fmac_f32_e32 v92, v23, v36
	v_mov_b32_e32 v23, v92
	v_lshlrev_b32_e32 v92, 16, v82
	v_mul_f32_e32 v92, v37, v92
	v_fmac_f32_e32 v92, v16, v36
	v_mov_b32_e32 v16, v92
	v_and_b32_e32 v92, 0xffff0000, v82
	v_mul_f32_e32 v92, v37, v92
	v_fmac_f32_e32 v92, v17, v36
	v_mov_b32_e32 v17, v92
	v_lshlrev_b32_e32 v92, 16, v83
	v_mul_f32_e32 v92, v37, v92
	v_fmac_f32_e32 v92, v18, v36
	v_mov_b32_e32 v18, v92
	v_and_b32_e32 v92, 0xffff0000, v83
	v_mul_f32_e32 v92, v37, v92
	v_fmac_f32_e32 v92, v19, v36
	v_mov_b32_e32 v19, v92
	v_lshlrev_b32_e32 v92, 16, v84
	v_mul_f32_e32 v92, v37, v92
	v_fmac_f32_e32 v92, v12, v36
	v_mov_b32_e32 v12, v92
	v_and_b32_e32 v92, 0xffff0000, v84
	v_mul_f32_e32 v92, v37, v92
	v_fmac_f32_e32 v92, v13, v36
	v_mov_b32_e32 v13, v92
	v_lshlrev_b32_e32 v92, 16, v85
	v_mul_f32_e32 v92, v37, v92
	v_fmac_f32_e32 v92, v14, v36
	v_mov_b32_e32 v14, v92
	v_and_b32_e32 v92, 0xffff0000, v85
	v_mul_f32_e32 v92, v37, v92
	v_fmac_f32_e32 v92, v15, v36
	v_mov_b32_e32 v15, v92
	v_lshlrev_b32_e32 v92, 16, v86
	v_mul_f32_e32 v92, v37, v92
	v_fmac_f32_e32 v92, v8, v36
	v_mov_b32_e32 v8, v92
	v_and_b32_e32 v92, 0xffff0000, v86
	v_mul_f32_e32 v92, v37, v92
	v_fmac_f32_e32 v92, v9, v36
	v_mov_b32_e32 v9, v92
	v_lshlrev_b32_e32 v92, 16, v87
	v_mul_f32_e32 v92, v37, v92
	v_fmac_f32_e32 v92, v10, v36
	v_mov_b32_e32 v10, v92
	v_and_b32_e32 v92, 0xffff0000, v87
	v_mul_f32_e32 v92, v37, v92
	v_fmac_f32_e32 v92, v11, v36
	v_mov_b32_e32 v11, v92
	v_lshlrev_b32_e32 v92, 16, v88
	v_mul_f32_e32 v92, v37, v92
	v_fmac_f32_e32 v92, v4, v36
	v_mov_b32_e32 v4, v92
	v_and_b32_e32 v92, 0xffff0000, v88
	v_mul_f32_e32 v92, v37, v92
	v_fmac_f32_e32 v92, v5, v36
	v_mov_b32_e32 v5, v92
	v_lshlrev_b32_e32 v92, 16, v89
	v_mul_f32_e32 v92, v37, v92
	v_fmac_f32_e32 v92, v6, v36
	v_mov_b32_e32 v6, v92
	v_and_b32_e32 v92, 0xffff0000, v89
	v_mul_f32_e32 v92, v37, v92
	v_fmac_f32_e32 v92, v7, v36
	v_mov_b32_e32 v7, v92
	v_lshlrev_b32_e32 v92, 16, v90
	v_mul_f32_e32 v92, v37, v92
	v_fmac_f32_e32 v92, v0, v36
	v_mov_b32_e32 v0, v92
	v_and_b32_e32 v92, 0xffff0000, v90
	v_mul_f32_e32 v92, v37, v92
	v_fmac_f32_e32 v92, v1, v36
	v_mov_b32_e32 v1, v92
	v_lshlrev_b32_e32 v92, 16, v91
	v_mul_f32_e32 v92, v37, v92
	v_fmac_f32_e32 v92, v2, v36
	v_mov_b32_e32 v2, v92
	v_and_b32_e32 v92, 0xffff0000, v91
	v_mul_f32_e32 v92, v37, v92
	v_fmac_f32_e32 v92, v3, v36
	v_mov_b32_e32 v3, v92
	s_lshl_b32 s38, s34, 16
	s_add_u32 s38, s96, s38
	s_addc_u32 s39, s97, 0
	global_store_dwordx4 v142, v[28:31], s[38:39]
	global_store_dwordx4 v142, v[24:27], s[38:39] offset:64
	global_store_dwordx4 v142, v[20:23], s[38:39] offset:128
	global_store_dwordx4 v142, v[16:19], s[38:39] offset:192
	global_store_dwordx4 v142, v[12:15], s[38:39] offset:256
	global_store_dwordx4 v142, v[8:11], s[38:39] offset:320
	global_store_dwordx4 v142, v[4:7], s[38:39] offset:384
	global_store_dwordx4 v142, v[0:3], s[38:39] offset:448
